# attention: s_setprio 3 (instead of 1) for blocks >= 256
# speedup vs baseline: 1.0051x; 1.0051x over previous
; DI void phase_even_c(const Ctx& c, int l, bf16* lds) {
;     ...
;   xcd_items(512, [&](int it) { attn_item(c, it, lds); });
.Lattn_pre:
	v_readlane_b32 vcc_lo, v252, 32
	s_cmp_ge_u32 vcc_lo, 0x10000
	s_cbranch_scc0 .Lattn_noprio
	s_setprio 3
